# sweep 2 far tiles: interleaved MFMAs front-loaded within the softmax segments (last MFMA at 60% instead of 86-88%)
# baseline (speedup 1.0000x reference)
; #define SBAR() __builtin_amdgcn_sched_barrier(0)
; template <bool DIFF>
; __device__ __forceinline__ void qkt(f32x16& a, f32x16& b, const char* Ks, const char* Qs, int krow, int r32, int hi) {
;   a = f32x16{}; b = f32x16{};
; #pragma unroll
;   for (int d = 0; d < 4; ++d) {
;     const int cb0 = (d * 16 + hi * 8) * 2, cb1 = ((d + 4) * 16 + hi * 8) * 2;
;     const bf16x8 k0 = *reinterpret_cast<const bf16x8*>(Ks + KSWZ(krow, cb0)), q0 = *reinterpret_cast<const bf16x8*>(Qs + KSWZ(r32, cb0));
;     const bf16x8 k1 = *reinterpret_cast<const bf16x8*>(Ks + KSWZ(krow, cb1)), q1 = *reinterpret_cast<const bf16x8*>(Qs + KSWZ(r32, cb1));
;     a = __builtin_amdgcn_mfma_f32_32x32x16_bf16(k0, q0, a, 0, 0, 0);
;     b = __builtin_amdgcn_mfma_f32_32x32x16_bf16(k1, q1, b, 0, 0, 0); }
; template <bool DIFF> ...
;     ...
;       BIAS_APPLY(t, 0, a0, b0, cb0);
;       { const float x1 = fmaf(cb0, C, e1), x2 = fmaf(cb0, C, e2);
; #pragma unroll
;       for (int r = 0; r < 16; ++r) a0[r] = __builtin_amdgcn_exp2f(fmaf(a0[r], C, x1));
;       if (DIFF) {
; #pragma unroll
;         for (int r = 0; r < 16; ++r) a0[r] = fmaf(nsg, __builtin_amdgcn_exp2f(fmaf(b0[r], C, x2)), a0[r]);
;       } }
;       PK4(a0, 0, pa0); PK4(a0, 8, pa1);
;       SBAR();
;       pv_step<0>(o, vb0, pa0); pv_step<1>(o, vb0, pa1);
.Lsw2f:
	ds_read_b128 v[64:67], v176
	ds_read_b128 v[68:71], v172 offset:36864
	ds_read_b128 v[72:75], v177
	ds_read_b128 v[76:79], v176 offset:8192
	s_waitcnt lgkmcnt(2)
	v_mfma_f32_32x32x16_bf16 v[112:127], v[64:67], v[68:71], 0
	ds_read_b128 v[64:67], v171 offset:36864
	ds_read_b128 v[128:131], v177 offset:8192
	s_waitcnt lgkmcnt(1)
	v_mfma_f32_32x32x16_bf16 v[96:111], v[72:75], v[64:67], 0
	ds_read_b128 v[72:75], v178
	ds_read_b128 v[132:135], v170 offset:36864
	ds_read_b128 v[80:83], v179
	ds_read_b128 v[136:139], v178 offset:8192
	ds_read_b128 v[140:143], v169 offset:36864
	ds_read_b128 v[192:195], v179 offset:8192
	s_waitcnt lgkmcnt(1)
	v_mfma_f32_32x32x16_bf16 v[96:111], v[80:83], v[140:143], v[96:111]
	v_mfma_f32_32x32x16_bf16 v[112:127], v[72:75], v[132:135], v[112:127]
	ds_read_b128 v[72:75], v180
	ds_read_b128 v[196:199], v168 offset:36864
	ds_read_b128 v[80:83], v181
	ds_read_b128 v[200:203], v180 offset:8192
	ds_read_b128 v[204:207], v167 offset:36864
	ds_read_b128 v[210:213], v181 offset:8192
	s_waitcnt lgkmcnt(1)
	v_mfma_f32_32x32x16_bf16 v[96:111], v[80:83], v[204:207], v[96:111]
	v_mfma_f32_32x32x16_bf16 v[112:127], v[72:75], v[196:199], v[112:127]
	ds_read_b128 v[72:75], v182
	ds_read_b128 v[214:217], v166 offset:36864
	ds_read_b128 v[80:83], v183
	ds_read_b128 v[218:221], v182 offset:8192
	ds_read_b128 v[222:225], v149 offset:36864
	ds_read_b128 v[226:229], v183 offset:8192
	s_waitcnt lgkmcnt(1)
	v_mfma_f32_32x32x16_bf16 v[96:111], v[80:83], v[222:225], v[96:111]
	v_mfma_f32_32x32x16_bf16 v[112:127], v[72:75], v[214:217], v[112:127]
	s_waitcnt lgkmcnt(0)
	v_mfma_f32_32x32x16_bf16 v[80:95], v[76:79], v[68:71], 0
	v_fmamk_f32 v235, v234, 0x3e38aa3b, v188
	v_fmamk_f32 v234, v234, 0x3e38aa3b, v187
	s_nop 8
	v_fmamk_f32 v112, v112, 0x3e38aa3b, v235
	v_fmamk_f32 v113, v113, 0x3e38aa3b, v235
	v_fmamk_f32 v114, v114, 0x3e38aa3b, v235
	v_fmamk_f32 v115, v115, 0x3e38aa3b, v235
	v_fmamk_f32 v116, v116, 0x3e38aa3b, v235
	v_fmamk_f32 v117, v117, 0x3e38aa3b, v235
	v_fmamk_f32 v96, v96, 0x3e38aa3b, v234
	v_mfma_f32_32x32x16_bf16 v[64:79], v[128:131], v[64:67], 0
	v_fmamk_f32 v97, v97, 0x3e38aa3b, v234
	v_fmamk_f32 v98, v98, 0x3e38aa3b, v234
	v_fmamk_f32 v99, v99, 0x3e38aa3b, v234
	v_fmamk_f32 v100, v100, 0x3e38aa3b, v234
	v_fmamk_f32 v101, v101, 0x3e38aa3b, v234
	v_exp_f32_e32 v112, v112
	v_exp_f32_e32 v113, v113
	v_exp_f32_e32 v114, v114
	v_mfma_f32_32x32x16_bf16 v[80:95], v[136:139], v[132:135], v[80:95]
	v_exp_f32_e32 v115, v115
	v_exp_f32_e32 v116, v116
	v_exp_f32_e32 v117, v117
	v_fmamk_f32 v118, v118, 0x3e38aa3b, v235
	v_fmamk_f32 v119, v119, 0x3e38aa3b, v235
	v_fmamk_f32 v120, v120, 0x3e38aa3b, v235
	v_fmamk_f32 v121, v121, 0x3e38aa3b, v235
	v_fmamk_f32 v122, v122, 0x3e38aa3b, v235
	v_fmamk_f32 v123, v123, 0x3e38aa3b, v235
	v_mfma_f32_32x32x16_bf16 v[64:79], v[192:195], v[140:143], v[64:79]
	v_lshl_add_u64 v[128:129], v[150:151], 0, s[34:35]
	v_add_co_u32_e32 v130, vcc, s70, v128
	s_nop 1
	v_addc_co_u32_e32 v131, vcc, 0, v129, vcc
	v_add_co_u32_e32 v132, vcc, s71, v128
	v_lshl_add_u64 v[136:137], v[152:153], 0, s[34:35]
	s_nop 0
	v_addc_co_u32_e32 v133, vcc, 0, v129, vcc
	v_add_co_u32_e32 v138, vcc, s72, v136
	s_nop 1
	v_addc_co_u32_e32 v139, vcc, 0, v137, vcc
	v_add_co_u32_e32 v140, vcc, s73, v136
	global_load_dwordx4 v[128:131], v[130:131], off
	s_nop 0
	global_load_dwordx4 v[132:135], v[132:133], off
	v_addc_co_u32_e32 v141, vcc, 0, v137, vcc
	global_load_dwordx4 v[136:139], v[138:139], off
	s_nop 0
	global_load_dwordx4 v[140:143], v[140:141], off
	v_fmamk_f32 v124, v124, 0x3e38aa3b, v235
	v_fmamk_f32 v125, v125, 0x3e38aa3b, v235
	v_fmamk_f32 v126, v126, 0x3e38aa3b, v235
	v_fmac_f32_e32 v235, 0x3e38aa3b, v127
	v_exp_f32_e32 v96, v96
	v_exp_f32_e32 v97, v97
	v_exp_f32_e32 v98, v98
	v_exp_f32_e32 v99, v99
	v_mfma_f32_32x32x16_bf16 v[80:95], v[200:203], v[196:199], v[80:95]
	v_exp_f32_e32 v100, v100
	v_exp_f32_e32 v101, v101
	v_fmamk_f32 v102, v102, 0x3e38aa3b, v234
	v_fmamk_f32 v103, v103, 0x3e38aa3b, v234
	v_fmamk_f32 v104, v104, 0x3e38aa3b, v234
	v_fmamk_f32 v105, v105, 0x3e38aa3b, v234
	v_fmamk_f32 v106, v106, 0x3e38aa3b, v234
	v_fmamk_f32 v107, v107, 0x3e38aa3b, v234
	v_fmamk_f32 v108, v108, 0x3e38aa3b, v234
	v_mfma_f32_32x32x16_bf16 v[64:79], v[210:213], v[204:207], v[64:79]
	v_fmamk_f32 v109, v109, 0x3e38aa3b, v234
	v_fmamk_f32 v110, v110, 0x3e38aa3b, v234
	v_fmac_f32_e32 v234, 0x3e38aa3b, v111
	v_exp_f32_e32 v118, v118
	v_exp_f32_e32 v119, v119
	v_exp_f32_e32 v120, v120
	v_exp_f32_e32 v121, v121
	v_mfma_f32_32x32x16_bf16 v[80:95], v[218:221], v[214:217], v[80:95]
	v_exp_f32_e32 v122, v122
	v_exp_f32_e32 v123, v123
	v_exp_f32_e32 v124, v124
	v_exp_f32_e32 v125, v125
	v_exp_f32_e32 v126, v126
	v_exp_f32_e32 v127, v235
	v_mfma_f32_32x32x16_bf16 v[64:79], v[226:229], v[222:225], v[64:79]
	v_exp_f32_e32 v102, v102
	v_exp_f32_e32 v103, v103
	v_exp_f32_e32 v104, v104
	v_exp_f32_e32 v105, v105
	v_exp_f32_e32 v106, v106
	v_exp_f32_e32 v107, v107
	v_exp_f32_e32 v108, v108
	v_exp_f32_e32 v109, v109
	v_exp_f32_e32 v110, v110
	v_exp_f32_e32 v111, v234
	v_pk_fma_f32 v[96:97], v[144:145], v[96:97], v[112:113]
	v_pk_fma_f32 v[98:99], v[144:145], v[98:99], v[114:115]
	v_pk_fma_f32 v[100:101], v[144:145], v[100:101], v[116:117]
	v_pk_fma_f32 v[102:103], v[144:145], v[102:103], v[118:119]
	v_pk_fma_f32 v[104:105], v[144:145], v[104:105], v[120:121]
	v_pk_fma_f32 v[106:107], v[144:145], v[106:107], v[122:123]
	v_pk_fma_f32 v[108:109], v[144:145], v[108:109], v[124:125]
	v_pk_fma_f32 v[110:111], v[144:145], v[110:111], v[126:127]
	v_cvt_pk_bf16_f32 v96, v96, v97
	v_cvt_pk_bf16_f32 v97, v98, v99
	v_cvt_pk_bf16_f32 v98, v100, v101
; #define SBAR() __builtin_amdgcn_sched_barrier(0)
; template <int KS> __device__ __forceinline__ void pv_step(f32x16* o, int vb, bf16x8 pa) {
;   const s16x4 l0 = tr_read<v_rd_off(0, KS, 0)>(vb), h0 = tr_read<v_rd_off(0, KS, 1)>(vb), l1 = tr_read<v_rd_off(1, KS, 0)>(vb), h1 = tr_read<v_rd_off(1, KS, 1)>(vb);
;   const s16x4 l2 = tr_read<v_rd_off(2, KS, 0)>(vb), h2 = tr_read<v_rd_off(2, KS, 1)>(vb), l3 = tr_read<v_rd_off(3, KS, 0)>(vb), h3 = tr_read<v_rd_off(3, KS, 1)>(vb);
;   asm volatile("s_waitcnt lgkmcnt(0)" ::: "memory"); SBAR();
;     ...
;   o[0] = __builtin_amdgcn_mfma_f32_32x32x16_bf16(pa, PK(l0, h0), o[0], 0, 0, 0);
;   o[1] = __builtin_amdgcn_mfma_f32_32x32x16_bf16(pa, PK(l1, h1), o[1], 0, 0, 0);
;   o[2] = __builtin_amdgcn_mfma_f32_32x32x16_bf16(pa, PK(l2, h2), o[2], 0, 0, 0);
;   o[3] = __builtin_amdgcn_mfma_f32_32x32x16_bf16(pa, PK(l3, h3), o[3], 0, 0, 0);
;     ...
; }
; template <bool DIFF> ...
;     ...
;       PK4(a0, 0, pa0); PK4(a0, 8, pa1);
;       SBAR();
;       pv_step<0>(o, vb0, pa0); pv_step<1>(o, vb0, pa1);
;       SBAR();
;       BIAS_APPLY(t, 1, a1, b1, cb1);
;       { const float x1 = fmaf(cb1, C, e1), x2 = fmaf(cb1, C, e2);
; #pragma unroll
;       for (int r = 0; r < 16; ++r) a1[r] = __builtin_amdgcn_exp2f(fmaf(a1[r], C, x1));
;       if (DIFF) {
; #pragma unroll
;         for (int r = 0; r < 16; ++r) a1[r] = fmaf(nsg, __builtin_amdgcn_exp2f(fmaf(b1[r], C, x2)), a1[r]);
;       } }
;       PK4(a1, 0, pa2); PK4(a1, 8, pa3);
;       SBAR();
;       pv_step<2>(o, vb0, pa2); pv_step<3>(o, vb0, pa3);
	v_cvt_pk_bf16_f32 v99, v102, v103
	s_nop 0
	v_permlane32_swap_b32_e32 v96, v98
	v_cvt_pk_bf16_f32 v100, v104, v105
	v_cvt_pk_bf16_f32 v101, v106, v107
	v_cvt_pk_bf16_f32 v102, v108, v109
	v_cvt_pk_bf16_f32 v103, v110, v111
	v_permlane32_swap_b32_e32 v97, v99
	v_permlane32_swap_b32_e32 v100, v102
	v_permlane32_swap_b32_e32 v101, v103
	ds_read_b64_tr_b16 v[104:105], v146 offset:0
	ds_read_b64_tr_b16 v[106:107], v146 offset:0x800
	ds_read_b64_tr_b16 v[108:109], v146 offset:0x200
	ds_read_b64_tr_b16 v[110:111], v146 offset:0xa00
	ds_read_b64_tr_b16 v[112:113], v146 offset:0x400
	ds_read_b64_tr_b16 v[114:115], v146 offset:0xc00
	ds_read_b64_tr_b16 v[116:117], v146 offset:0x600
	ds_read_b64_tr_b16 v[118:119], v146 offset:0xe00
	ds_read_b64_tr_b16 v[238:239], v146 offset:0x1000
	ds_read_b64_tr_b16 v[240:241], v146 offset:0x1800
	ds_read_b64_tr_b16 v[242:243], v146 offset:0x1200
	ds_read_b64_tr_b16 v[244:245], v146 offset:0x1a00
	ds_read_b64_tr_b16 v[246:247], v146 offset:0x1400
	ds_read_b64_tr_b16 v[248:249], v146 offset:0x1c00
	ds_read_b64_tr_b16 v[120:121], v146 offset:0x1600
	ds_read_b64_tr_b16 v[122:123], v146 offset:0x1e00
	v_fmamk_f32 v237, v236, 0x3e38aa3b, v188
	v_fmamk_f32 v236, v236, 0x3e38aa3b, v187
	v_fmamk_f32 v80, v80, 0x3e38aa3b, v237
	v_fmamk_f32 v81, v81, 0x3e38aa3b, v237
	v_fmamk_f32 v82, v82, 0x3e38aa3b, v237
	v_fmamk_f32 v83, v83, 0x3e38aa3b, v237
	v_fmamk_f32 v84, v84, 0x3e38aa3b, v237
	v_fmamk_f32 v85, v85, 0x3e38aa3b, v237
	v_fmamk_f32 v86, v86, 0x3e38aa3b, v237
	v_fmamk_f32 v87, v87, 0x3e38aa3b, v237
	s_waitcnt lgkmcnt(0)
	ds_read_b64_tr_b16 v[192:193], v146 offset:0x2000
	ds_read_b64_tr_b16 v[194:195], v146 offset:0x2800
	ds_read_b64_tr_b16 v[196:197], v146 offset:0x2200
	ds_read_b64_tr_b16 v[198:199], v146 offset:0x2a00
	ds_read_b64_tr_b16 v[200:201], v146 offset:0x2400
	ds_read_b64_tr_b16 v[202:203], v146 offset:0x2c00
	ds_read_b64_tr_b16 v[204:205], v146 offset:0x2600
	ds_read_b64_tr_b16 v[206:207], v146 offset:0x2e00
	ds_read_b64_tr_b16 v[210:211], v146 offset:0x3000
	ds_read_b64_tr_b16 v[212:213], v146 offset:0x3800
	ds_read_b64_tr_b16 v[214:215], v146 offset:0x3200
	ds_read_b64_tr_b16 v[216:217], v146 offset:0x3a00
	ds_read_b64_tr_b16 v[218:219], v146 offset:0x3400
	ds_read_b64_tr_b16 v[220:221], v146 offset:0x3c00
	ds_read_b64_tr_b16 v[222:223], v146 offset:0x3600
	ds_read_b64_tr_b16 v[224:225], v146 offset:0x3e00
	v_mfma_f32_32x32x16_bf16 v[0:15], v[96:99], v[104:107], v[0:15]
	v_fmamk_f32 v88, v88, 0x3e38aa3b, v237
	v_fmamk_f32 v89, v89, 0x3e38aa3b, v237
	v_fmamk_f32 v90, v90, 0x3e38aa3b, v237
	v_fmamk_f32 v91, v91, 0x3e38aa3b, v237
	v_fmamk_f32 v92, v92, 0x3e38aa3b, v237
	v_fmamk_f32 v93, v93, 0x3e38aa3b, v237
	v_fmamk_f32 v94, v94, 0x3e38aa3b, v237
	v_fmac_f32_e32 v237, 0x3e38aa3b, v95
	v_fmamk_f32 v64, v64, 0x3e38aa3b, v236
	v_fmamk_f32 v65, v65, 0x3e38aa3b, v236
	v_mfma_f32_32x32x16_bf16 v[16:31], v[96:99], v[108:111], v[16:31]
	v_fmamk_f32 v66, v66, 0x3e38aa3b, v236
	v_fmamk_f32 v67, v67, 0x3e38aa3b, v236
	v_fmamk_f32 v68, v68, 0x3e38aa3b, v236
	v_fmamk_f32 v69, v69, 0x3e38aa3b, v236
	v_fmamk_f32 v70, v70, 0x3e38aa3b, v236
	v_fmamk_f32 v71, v71, 0x3e38aa3b, v236
	v_fmamk_f32 v72, v72, 0x3e38aa3b, v236
	v_fmamk_f32 v73, v73, 0x3e38aa3b, v236
	v_fmamk_f32 v74, v74, 0x3e38aa3b, v236
	v_fmamk_f32 v75, v75, 0x3e38aa3b, v236
	v_mfma_f32_32x32x16_bf16 v[32:47], v[96:99], v[112:115], v[32:47]
	v_fmamk_f32 v76, v76, 0x3e38aa3b, v236
	v_fmamk_f32 v77, v77, 0x3e38aa3b, v236
	v_fmamk_f32 v78, v78, 0x3e38aa3b, v236
	v_fmac_f32_e32 v236, 0x3e38aa3b, v79
	v_exp_f32_e32 v80, v80
	v_exp_f32_e32 v81, v81
	v_exp_f32_e32 v82, v82
	v_mfma_f32_32x32x16_bf16 v[48:63], v[96:99], v[116:119], v[48:63]
	v_exp_f32_e32 v83, v83
	v_exp_f32_e32 v84, v84
	v_exp_f32_e32 v85, v85
	v_exp_f32_e32 v86, v86
	v_exp_f32_e32 v87, v87
	v_mfma_f32_32x32x16_bf16 v[0:15], v[100:103], v[238:241], v[0:15]
	v_exp_f32_e32 v88, v88
	v_exp_f32_e32 v89, v89
	v_exp_f32_e32 v90, v90
	v_exp_f32_e32 v91, v91
	v_exp_f32_e32 v92, v92
	v_mfma_f32_32x32x16_bf16 v[16:31], v[100:103], v[242:245], v[16:31]
	v_exp_f32_e32 v93, v93
	v_exp_f32_e32 v94, v94
	v_exp_f32_e32 v95, v237
	v_exp_f32_e32 v64, v64
	v_exp_f32_e32 v65, v65
	v_mfma_f32_32x32x16_bf16 v[32:47], v[100:103], v[246:249], v[32:47]
	v_exp_f32_e32 v66, v66
	v_exp_f32_e32 v67, v67
	v_exp_f32_e32 v68, v68
	v_exp_f32_e32 v69, v69
	v_exp_f32_e32 v70, v70
	v_mfma_f32_32x32x16_bf16 v[48:63], v[100:103], v[120:123], v[48:63]
	v_exp_f32_e32 v71, v71
	v_exp_f32_e32 v72, v72
	v_exp_f32_e32 v73, v73
	v_exp_f32_e32 v74, v74
	v_exp_f32_e32 v75, v75
	v_exp_f32_e32 v76, v76
	v_exp_f32_e32 v77, v77
	v_exp_f32_e32 v78, v78
	v_exp_f32_e32 v79, v236
	v_pk_fma_f32 v[64:65], v[144:145], v[64:65], v[80:81]
	v_pk_fma_f32 v[66:67], v[144:145], v[66:67], v[82:83]
	v_pk_fma_f32 v[68:69], v[144:145], v[68:69], v[84:85]
	v_pk_fma_f32 v[70:71], v[144:145], v[70:71], v[86:87]
	v_pk_fma_f32 v[72:73], v[144:145], v[72:73], v[88:89]
	v_pk_fma_f32 v[74:75], v[144:145], v[74:75], v[90:91]
	v_pk_fma_f32 v[76:77], v[144:145], v[76:77], v[92:93]
	v_pk_fma_f32 v[78:79], v[144:145], v[78:79], v[94:95]
	v_cvt_pk_bf16_f32 v64, v64, v65
	v_cvt_pk_bf16_f32 v65, v66, v67
	v_cvt_pk_bf16_f32 v66, v68, v69
	v_cvt_pk_bf16_f32 v67, v70, v71
	v_cvt_pk_bf16_f32 v68, v72, v73
	v_cvt_pk_bf16_f32 v69, v74, v75
	v_cvt_pk_bf16_f32 v70, v76, v77
	v_cvt_pk_bf16_f32 v71, v78, v79
	v_permlane32_swap_b32_e32 v64, v66
	v_permlane32_swap_b32_e32 v65, v67
	v_permlane32_swap_b32_e32 v68, v70
	v_permlane32_swap_b32_e32 v69, v71
	s_waitcnt lgkmcnt(0)
	v_mfma_f32_32x32x16_bf16 v[0:15], v[64:67], v[192:195], v[0:15]
	v_mfma_f32_32x32x16_bf16 v[16:31], v[64:67], v[196:199], v[16:31]
	v_mfma_f32_32x32x16_bf16 v[32:47], v[64:67], v[200:203], v[32:47]
	v_mfma_f32_32x32x16_bf16 v[48:63], v[64:67], v[204:207], v[48:63]
	v_mfma_f32_32x32x16_bf16 v[0:15], v[68:71], v[210:213], v[0:15]
	s_add_u32 s34, s34, 0x20000
	s_addc_u32 s35, s35, 0
	v_add_u32_e32 v173, 64, v173
	s_add_i32 s93, s93, 64
	s_cmp_eq_u32 s2, s34
	v_mfma_f32_32x32x16_bf16 v[16:31], v[68:71], v[214:217], v[16:31]
	v_mfma_f32_32x32x16_bf16 v[32:47], v[68:71], v[218:221], v[32:47]
	v_mfma_f32_32x32x16_bf16 v[48:63], v[68:71], v[222:225], v[48:63]
	s_cbranch_scc1 .LBB0_326
	s_branch .LBB0_310
